# acquire invalidate issued by wave 0 at the start of each seam instead of after the arrival atomic
# speedup vs baseline: 1.0075x; 1.0075x over previous
; __device__ __forceinline__ unsigned xb_ld(unsigned* p)              { return __hip_atomic_load(p, __ATOMIC_RELAXED, __HIP_MEMORY_SCOPE_AGENT); }
; __device__ __forceinline__ void xcd_barrier_complete(unsigned* bar, unsigned x, unsigned& nloc, unsigned& nx) {
;     const unsigned G = gridDim.x * gridDim.y * gridDim.z;
;     unsigned sum, cnt, mine, sp = 0u;
;     for (;;) {
;         sum = 0u; cnt = 0u; mine = 0u;
; #pragma unroll
;         for (unsigned j = 0; j < 16; ++j) { const unsigned c = xb_ld(&bar[XB_XCNT(j)]); sum += c; cnt += (c > 0u) ? 1u : 0u; mine = (j == x) ? c : mine; }
; __device__ __forceinline__ void xcd_barrier(const XcdBarrier& b) {
;     asm volatile("s_waitcnt vmcnt(0)" ::: "memory");
;     __syncthreads();
;     if (threadIdx.x == 0) {
;         unsigned* bar = b.bar;
;         __builtin_amdgcn_s_waitcnt(0);
;         unsigned nloc = b.st[0], nx = b.st[1];
;         if (nloc == 0u) { xcd_barrier_complete(bar, b.x, nloc, nx); b.st[0] = nloc; b.st[1] = nx; }
.LBB0_121:
	s_cmp_lt_i32 s85, 2
	s_cbranch_scc1 .LBB0_175
	v_readfirstlane_b32 s3, v254
	s_cmp_lt_u32 s3, 64
	s_cbranch_scc0 .Lseam_noinv_0
	buffer_inv sc1
.Lseam_noinv_0:
	s_waitcnt vmcnt(0)
	s_waitcnt lgkmcnt(0)
	s_barrier
	s_mov_b64 s[4:5], exec
	v_readlane_b32 s6, v255, 1
	v_readlane_b32 s7, v255, 2
	s_and_b64 s[6:7], s[4:5], s[6:7]
	s_mov_b64 exec, s[6:7]
	s_cbranch_execz .LBB0_174
	s_add_i32 s3, 0, 0x23fc0
	v_mov_b32_e32 v0, s3
	s_waitcnt vmcnt(0) expcnt(0) lgkmcnt(0)
	ds_read_b32 v2, v0
	s_add_i32 s3, 0, 0x23fc4
	v_mov_b32_e32 v0, s3
	ds_read_b32 v0, v0
	s_waitcnt lgkmcnt(1)
	v_cmp_ne_u32_e32 vcc, 0, v2
	s_cbranch_vccnz .LBB0_138
	s_add_u32 s6, s30, 0x80200
	s_addc_u32 s7, s31, 0
	s_add_u32 s8, s30, 0x80400
	s_addc_u32 s9, s31, 0
	s_add_u32 s10, s30, 0x80500
	s_addc_u32 s11, s31, 0
	s_add_u32 s12, s30, 0x80600
	s_addc_u32 s13, s31, 0
	s_add_u32 s14, s30, 0x80700
	s_addc_u32 s15, s31, 0
	s_add_u32 s16, s30, 0x80800
	s_addc_u32 s17, s31, 0
	s_add_u32 s18, s30, 0x80900
	s_addc_u32 s19, s31, 0
	s_add_u32 s20, s30, 0x80a00
	s_addc_u32 s21, s31, 0
	s_add_u32 s22, s30, 0x80b00
	s_addc_u32 s23, s31, 0
	s_add_u32 s24, s30, 0x80c00
	s_addc_u32 s25, s31, 0
	s_add_u32 s26, s30, 0x80d00
	s_addc_u32 s27, s31, 0
	s_add_u32 s36, s30, 0x80e00
	s_addc_u32 s37, s31, 0
	s_add_u32 s38, s30, 0x80f00
	s_addc_u32 s39, s31, 0
	s_add_u32 s42, s30, 0x81000
	s_load_dword s3, s[0:1], 0x118
	s_addc_u32 s43, s31, 0
	s_add_u32 s48, s30, 0x81100
	s_addc_u32 s49, s31, 0
	s_add_u32 s54, s30, 0x81200
	s_addc_u32 s55, s31, 0
	s_waitcnt lgkmcnt(0)
	s_mul_i32 s3, s87, s3
	s_add_u32 s58, s30, 0x81300
	s_mul_i32 s3, s3, s86
	s_addc_u32 s59, s31, 0
	s_mov_b32 s28, 1
	v_mov_b32_e32 v16, 0
	s_branch .LBB0_126

; __device__ __forceinline__ void xcd_barrier(const XcdBarrier& b) {
;     asm volatile("s_waitcnt vmcnt(0)" ::: "memory");
;     __syncthreads();
.LBB0_179:
	s_or_b64 exec, exec, s[6:7]
	s_cmp_lt_u32 s85, 3
	s_cbranch_scc1 .LBB0_233
	v_readfirstlane_b32 s3, v254
	s_cmp_lt_u32 s3, 64
	s_cbranch_scc0 .Lseam_noinv_1
	buffer_inv sc1

; __device__ __forceinline__ void xcd_barrier(const XcdBarrier& b) {
;     asm volatile("s_waitcnt vmcnt(0)" ::: "memory");
;     __syncthreads();
.LBB0_271:
	v_readfirstlane_b32 s3, v254
	s_cmp_lt_u32 s3, 64
	s_cbranch_scc0 .Lseam_noinv_2
	buffer_inv sc1

; __device__ __forceinline__ unsigned xb_ld(unsigned* p)              { return __hip_atomic_load(p, __ATOMIC_RELAXED, __HIP_MEMORY_SCOPE_AGENT); }
; __device__ __forceinline__ void xcd_barrier_complete(unsigned* bar, unsigned x, unsigned& nloc, unsigned& nx) {
;     const unsigned G = gridDim.x * gridDim.y * gridDim.z;
;     unsigned sum, cnt, mine, sp = 0u;
;     for (;;) {
;         sum = 0u; cnt = 0u; mine = 0u;
; #pragma unroll
;         for (unsigned j = 0; j < 16; ++j) { const unsigned c = xb_ld(&bar[XB_XCNT(j)]); sum += c; cnt += (c > 0u) ? 1u : 0u; mine = (j == x) ? c : mine; }
; __device__ __forceinline__ void xcd_barrier(const XcdBarrier& b) {
;     asm volatile("s_waitcnt vmcnt(0)" ::: "memory");
;     __syncthreads();
;     if (threadIdx.x == 0) {
;         unsigned* bar = b.bar;
;         __builtin_amdgcn_s_waitcnt(0);
;         unsigned nloc = b.st[0], nx = b.st[1];
;         if (nloc == 0u) { xcd_barrier_complete(bar, b.x, nloc, nx); b.st[0] = nloc; b.st[1] = nx; }
.LBB0_438:
	s_cmpk_eq_i32 s86, 0x100
	s_cbranch_scc1 .LBB0_492
	s_cmp_lt_i32 s85, 5
	s_cbranch_scc1 .LBB0_492
	v_readfirstlane_b32 s3, v254
	s_cmp_lt_u32 s3, 64
	s_cbranch_scc0 .Lseam_noinv_3
	buffer_inv sc1
.Lseam_noinv_3:
	s_waitcnt vmcnt(0)
	s_waitcnt vmcnt(0)
	s_barrier
	s_mov_b64 s[4:5], exec
	v_readlane_b32 s6, v255, 1
	v_readlane_b32 s7, v255, 2
	s_and_b64 s[6:7], s[4:5], s[6:7]
	s_mov_b64 exec, s[6:7]
	s_cbranch_execz .LBB0_491
	s_add_i32 s3, 0, 0x23fc0
	v_mov_b32_e32 v0, s3
	s_waitcnt vmcnt(0) expcnt(0) lgkmcnt(0)
	ds_read_b32 v2, v0
	s_add_i32 s3, 0, 0x23fc4
	v_mov_b32_e32 v0, s3
	ds_read_b32 v0, v0
	s_waitcnt lgkmcnt(1)
	v_cmp_ne_u32_e32 vcc, 0, v2
	s_cbranch_vccnz .LBB0_455
	s_add_u32 s6, s30, 0x80200
	s_addc_u32 s7, s31, 0
	s_add_u32 s8, s30, 0x80400
	s_addc_u32 s9, s31, 0
	s_add_u32 s10, s30, 0x80500
	s_addc_u32 s11, s31, 0
	s_add_u32 s12, s30, 0x80600
	s_addc_u32 s13, s31, 0
	s_add_u32 s14, s30, 0x80700
	s_addc_u32 s15, s31, 0
	s_add_u32 s16, s30, 0x80800
	s_addc_u32 s17, s31, 0
	s_add_u32 s18, s30, 0x80900
	s_addc_u32 s19, s31, 0
	s_add_u32 s20, s30, 0x80a00
	s_addc_u32 s21, s31, 0
	s_add_u32 s22, s30, 0x80b00
	s_addc_u32 s23, s31, 0
	s_add_u32 s24, s30, 0x80c00
	s_addc_u32 s25, s31, 0
	s_add_u32 s26, s30, 0x80d00
	s_addc_u32 s27, s31, 0
	s_add_u32 s36, s30, 0x80e00
	s_addc_u32 s37, s31, 0
	s_add_u32 s38, s30, 0x80f00
	s_addc_u32 s39, s31, 0
	s_add_u32 s42, s30, 0x81000
	s_load_dword s3, s[0:1], 0x118
	s_addc_u32 s43, s31, 0
	s_add_u32 s48, s30, 0x81100
	s_addc_u32 s49, s31, 0
	s_add_u32 s54, s30, 0x81200
	s_addc_u32 s55, s31, 0
	s_waitcnt lgkmcnt(0)
	s_mul_i32 s3, s87, s3
	s_add_u32 s58, s30, 0x81300
	s_mul_i32 s3, s3, s86
	s_addc_u32 s59, s31, 0
	s_mov_b32 s28, 1
	v_mov_b32_e32 v16, 0
	s_branch .LBB0_443

; __device__ __forceinline__ unsigned xb_ld(unsigned* p)              { return __hip_atomic_load(p, __ATOMIC_RELAXED, __HIP_MEMORY_SCOPE_AGENT); }
; __device__ __forceinline__ void xcd_barrier_complete(unsigned* bar, unsigned x, unsigned& nloc, unsigned& nx) {
;     const unsigned G = gridDim.x * gridDim.y * gridDim.z;
;     unsigned sum, cnt, mine, sp = 0u;
;     for (;;) {
;         sum = 0u; cnt = 0u; mine = 0u;
; #pragma unroll
;         for (unsigned j = 0; j < 16; ++j) { const unsigned c = xb_ld(&bar[XB_XCNT(j)]); sum += c; cnt += (c > 0u) ? 1u : 0u; mine = (j == x) ? c : mine; }
; __device__ __forceinline__ void xcd_barrier(const XcdBarrier& b) {
;     asm volatile("s_waitcnt vmcnt(0)" ::: "memory");
;     __syncthreads();
;     if (threadIdx.x == 0) {
;         unsigned* bar = b.bar;
;         __builtin_amdgcn_s_waitcnt(0);
;         unsigned nloc = b.st[0], nx = b.st[1];
;         if (nloc == 0u) { xcd_barrier_complete(bar, b.x, nloc, nx); b.st[0] = nloc; b.st[1] = nx; }
.LBB0_555:
	s_cmp_lt_i32 s85, 6
	s_cbranch_scc1 .LBB0_609
	v_readfirstlane_b32 s3, v254
	s_cmp_lt_u32 s3, 64
	s_cbranch_scc0 .Lseam_noinv_4
	buffer_inv sc1
.Lseam_noinv_4:
	s_waitcnt vmcnt(0)
	s_barrier
	s_mov_b64 s[4:5], exec
	v_readlane_b32 s6, v255, 1
	v_readlane_b32 s7, v255, 2
	s_and_b64 s[6:7], s[4:5], s[6:7]
	s_mov_b64 exec, s[6:7]
	s_cbranch_execz .LBB0_608
	s_add_i32 s3, 0, 0x23fc0
	v_mov_b32_e32 v0, s3
	s_waitcnt vmcnt(0) expcnt(0) lgkmcnt(0)
	ds_read_b32 v2, v0
	s_add_i32 s3, 0, 0x23fc4
	v_mov_b32_e32 v0, s3
	ds_read_b32 v0, v0
	s_waitcnt lgkmcnt(1)
	v_cmp_ne_u32_e32 vcc, 0, v2
	s_cbranch_vccnz .LBB0_572
	s_add_u32 s6, s30, 0x80200
	s_addc_u32 s7, s31, 0
	s_add_u32 s8, s30, 0x80400
	s_addc_u32 s9, s31, 0
	s_add_u32 s10, s30, 0x80500
	s_addc_u32 s11, s31, 0
	s_add_u32 s12, s30, 0x80600
	s_addc_u32 s13, s31, 0
	s_add_u32 s14, s30, 0x80700
	s_addc_u32 s15, s31, 0
	s_add_u32 s16, s30, 0x80800
	s_addc_u32 s17, s31, 0
	s_add_u32 s18, s30, 0x80900
	s_addc_u32 s19, s31, 0
	s_add_u32 s20, s30, 0x80a00
	s_addc_u32 s21, s31, 0
	s_add_u32 s22, s30, 0x80b00
	s_addc_u32 s23, s31, 0
	s_add_u32 s24, s30, 0x80c00
	s_addc_u32 s25, s31, 0
	s_add_u32 s26, s30, 0x80d00
	s_addc_u32 s27, s31, 0
	s_add_u32 s36, s30, 0x80e00
	s_addc_u32 s37, s31, 0
	s_add_u32 s38, s30, 0x80f00
	s_addc_u32 s39, s31, 0
	s_add_u32 s42, s30, 0x81000
	s_load_dword s3, s[0:1], 0x118
	s_addc_u32 s43, s31, 0
	s_add_u32 s48, s30, 0x81100
	s_addc_u32 s49, s31, 0
	s_add_u32 s54, s30, 0x81200
	s_addc_u32 s55, s31, 0
	s_waitcnt lgkmcnt(0)
	s_mul_i32 s3, s87, s3
	s_add_u32 s58, s30, 0x81300
	s_mul_i32 s3, s3, s86
	s_addc_u32 s59, s31, 0
	s_mov_b32 s28, 1
	v_mov_b32_e32 v16, 0
	s_branch .LBB0_560

; __device__ __forceinline__ unsigned xb_ld(unsigned* p)              { return __hip_atomic_load(p, __ATOMIC_RELAXED, __HIP_MEMORY_SCOPE_AGENT); }
; __device__ __forceinline__ void xcd_barrier_complete(unsigned* bar, unsigned x, unsigned& nloc, unsigned& nx) {
;     const unsigned G = gridDim.x * gridDim.y * gridDim.z;
;     unsigned sum, cnt, mine, sp = 0u;
;     for (;;) {
;         sum = 0u; cnt = 0u; mine = 0u;
; #pragma unroll
;         for (unsigned j = 0; j < 16; ++j) { const unsigned c = xb_ld(&bar[XB_XCNT(j)]); sum += c; cnt += (c > 0u) ? 1u : 0u; mine = (j == x) ? c : mine; }
; __device__ __forceinline__ void xcd_barrier(const XcdBarrier& b) {
;     asm volatile("s_waitcnt vmcnt(0)" ::: "memory");
;     __syncthreads();
;     if (threadIdx.x == 0) {
;         unsigned* bar = b.bar;
;         __builtin_amdgcn_s_waitcnt(0);
;         unsigned nloc = b.st[0], nx = b.st[1];
;         if (nloc == 0u) { xcd_barrier_complete(bar, b.x, nloc, nx); b.st[0] = nloc; b.st[1] = nx; }
.LBB0_650:
	s_or_b64 exec, exec, s[0:1]
	s_cmp_lt_i32 s85, 8
	s_cbranch_scc1 .LBB0_704
	v_readfirstlane_b32 s3, v254
	s_cmp_lt_u32 s3, 64
	s_cbranch_scc0 .Lseam_noinv_5
	buffer_inv sc1
.Lseam_noinv_5:
	s_waitcnt vmcnt(0)
	s_barrier
	s_mov_b64 s[0:1], exec
	v_readlane_b32 s4, v255, 1
	v_readlane_b32 s5, v255, 2
	s_and_b64 s[4:5], s[0:1], s[4:5]
	s_mov_b64 exec, s[4:5]
	s_cbranch_execz .LBB0_703
	s_add_i32 s3, 0, 0x23fc0
	v_mov_b32_e32 v0, s3
	s_waitcnt vmcnt(0) expcnt(0) lgkmcnt(0)
	ds_read_b32 v2, v0
	s_add_i32 s3, 0, 0x23fc4
	v_mov_b32_e32 v0, s3
	ds_read_b32 v0, v0
	s_waitcnt lgkmcnt(1)
	v_cmp_ne_u32_e32 vcc, 0, v2
	s_cbranch_vccnz .LBB0_667
	s_add_u32 s4, s30, 0x80200
	s_addc_u32 s5, s31, 0
	s_add_u32 s6, s30, 0x80400
	s_addc_u32 s7, s31, 0
	s_add_u32 s8, s30, 0x80500
	s_addc_u32 s9, s31, 0
	s_add_u32 s10, s30, 0x80600
	s_addc_u32 s11, s31, 0
	s_add_u32 s12, s30, 0x80700
	s_addc_u32 s13, s31, 0
	s_add_u32 s14, s30, 0x80800
	s_addc_u32 s15, s31, 0
	s_add_u32 s16, s30, 0x80900
	s_addc_u32 s17, s31, 0
	s_add_u32 s18, s30, 0x80a00
	s_addc_u32 s19, s31, 0
	s_add_u32 s20, s30, 0x80b00
	s_addc_u32 s21, s31, 0
	s_add_u32 s22, s30, 0x80c00
	s_addc_u32 s23, s31, 0
	s_add_u32 s24, s30, 0x80d00
	s_addc_u32 s25, s31, 0
	s_add_u32 s26, s30, 0x80e00
	s_addc_u32 s27, s31, 0
	s_add_u32 s36, s30, 0x80f00
	s_addc_u32 s37, s31, 0
	s_add_u32 s38, s30, 0x81000
	s_addc_u32 s39, s31, 0
	s_add_u32 s42, s30, 0x81100
	s_addc_u32 s43, s31, 0
	s_add_u32 s48, s30, 0x81200
	v_readlane_b32 s3, v255, 0
	s_addc_u32 s49, s31, 0
	s_mul_i32 s3, s87, s3
	s_add_u32 s54, s30, 0x81300
	s_mul_i32 s3, s3, s86
	s_addc_u32 s55, s31, 0
	s_mov_b32 s28, 1
	v_mov_b32_e32 v16, 0
	s_branch .LBB0_655

; __device__ __forceinline__ void xcd_barrier(const XcdBarrier& b) {
;     asm volatile("s_waitcnt vmcnt(0)" ::: "memory");
;     __syncthreads();
.Lp7_done:
	s_cmp_gt_i32 s85, 8
	s_cbranch_scc0 .LBB0_893
	v_readfirstlane_b32 s3, v254
	s_cmp_lt_u32 s3, 64
	s_cbranch_scc0 .Lseam_noinv_6
	buffer_inv sc1

; __device__ __forceinline__ unsigned xb_ld(unsigned* p)              { return __hip_atomic_load(p, __ATOMIC_RELAXED, __HIP_MEMORY_SCOPE_AGENT); }
; __device__ __forceinline__ void xcd_barrier_complete(unsigned* bar, unsigned x, unsigned& nloc, unsigned& nx) {
;     const unsigned G = gridDim.x * gridDim.y * gridDim.z;
;     unsigned sum, cnt, mine, sp = 0u;
;     for (;;) {
;         sum = 0u; cnt = 0u; mine = 0u;
; #pragma unroll
;         for (unsigned j = 0; j < 16; ++j) { const unsigned c = xb_ld(&bar[XB_XCNT(j)]); sum += c; cnt += (c > 0u) ? 1u : 0u; mine = (j == x) ? c : mine; }
; __device__ __forceinline__ void xcd_barrier(const XcdBarrier& b) {
;     asm volatile("s_waitcnt vmcnt(0)" ::: "memory");
;     __syncthreads();
;     if (threadIdx.x == 0) {
;         unsigned* bar = b.bar;
;         __builtin_amdgcn_s_waitcnt(0);
;         unsigned nloc = b.st[0], nx = b.st[1];
;         if (nloc == 0u) { xcd_barrier_complete(bar, b.x, nloc, nx); b.st[0] = nloc; b.st[1] = nx; }
.LBB0_1193:
	s_cmp_lt_i32 s85, 12
	s_cbranch_scc1 .LBB0_1247
	v_readfirstlane_b32 s3, v254
	s_cmp_lt_u32 s3, 64
	s_cbranch_scc0 .Lseam_noinv_8
	buffer_inv sc1
.Lseam_noinv_8:
	s_waitcnt vmcnt(0)
	s_waitcnt vmcnt(0) lgkmcnt(0)
	s_barrier
	s_mov_b64 s[0:1], exec
	v_readlane_b32 s4, v255, 1
	v_readlane_b32 s5, v255, 2
	s_and_b64 s[4:5], s[0:1], s[4:5]
	s_mov_b64 exec, s[4:5]
	s_cbranch_execz .LBB0_1246
	s_add_i32 s3, 0, 0x23fc0
	v_mov_b32_e32 v0, s3
	s_waitcnt vmcnt(0) expcnt(0) lgkmcnt(0)
	ds_read_b32 v2, v0
	s_add_i32 s3, 0, 0x23fc4
	v_mov_b32_e32 v0, s3
	ds_read_b32 v0, v0
	s_waitcnt lgkmcnt(1)
	v_cmp_ne_u32_e32 vcc, 0, v2
	s_cbranch_vccnz .LBB0_1210
	s_add_u32 s4, s30, 0x80200
	s_addc_u32 s5, s31, 0
	s_add_u32 s6, s30, 0x80400
	s_addc_u32 s7, s31, 0
	s_add_u32 s8, s30, 0x80500
	s_addc_u32 s9, s31, 0
	s_add_u32 s10, s30, 0x80600
	s_addc_u32 s11, s31, 0
	s_add_u32 s12, s30, 0x80700
	s_addc_u32 s13, s31, 0
	s_add_u32 s14, s30, 0x80800
	s_addc_u32 s15, s31, 0
	s_add_u32 s16, s30, 0x80900
	s_addc_u32 s17, s31, 0
	s_add_u32 s18, s30, 0x80a00
	s_addc_u32 s19, s31, 0
	s_add_u32 s20, s30, 0x80b00
	s_addc_u32 s21, s31, 0
	s_add_u32 s22, s30, 0x80c00
	s_addc_u32 s23, s31, 0
	s_add_u32 s24, s30, 0x80d00
	s_addc_u32 s25, s31, 0
	s_add_u32 s26, s30, 0x80e00
	s_addc_u32 s27, s31, 0
	s_add_u32 s36, s30, 0x80f00
	s_addc_u32 s37, s31, 0
	s_add_u32 s38, s30, 0x81000
	s_addc_u32 s39, s31, 0
	s_add_u32 s42, s30, 0x81100
	s_addc_u32 s43, s31, 0
	s_add_u32 s48, s30, 0x81200
	v_readlane_b32 s3, v255, 0
	s_addc_u32 s49, s31, 0
	s_mul_i32 s3, s87, s3
	s_add_u32 s52, s30, 0x81300
	s_mul_i32 s3, s3, s86
	s_addc_u32 s53, s31, 0
	s_mov_b32 s28, 1
	v_mov_b32_e32 v16, 0
	s_branch .LBB0_1198

; __device__ __forceinline__ unsigned xb_ld(unsigned* p)              { return __hip_atomic_load(p, __ATOMIC_RELAXED, __HIP_MEMORY_SCOPE_AGENT); }
; __device__ __forceinline__ void xcd_barrier_complete(unsigned* bar, unsigned x, unsigned& nloc, unsigned& nx) {
;     const unsigned G = gridDim.x * gridDim.y * gridDim.z;
;     unsigned sum, cnt, mine, sp = 0u;
;     for (;;) {
;         sum = 0u; cnt = 0u; mine = 0u;
; #pragma unroll
;         for (unsigned j = 0; j < 16; ++j) { const unsigned c = xb_ld(&bar[XB_XCNT(j)]); sum += c; cnt += (c > 0u) ? 1u : 0u; mine = (j == x) ? c : mine; }
; __device__ __forceinline__ void xcd_barrier(const XcdBarrier& b) {
;     asm volatile("s_waitcnt vmcnt(0)" ::: "memory");
;     __syncthreads();
;     if (threadIdx.x == 0) {
;         unsigned* bar = b.bar;
;         __builtin_amdgcn_s_waitcnt(0);
;         unsigned nloc = b.st[0], nx = b.st[1];
;         if (nloc == 0u) { xcd_barrier_complete(bar, b.x, nloc, nx); b.st[0] = nloc; b.st[1] = nx; }
.LBB0_1251:
	s_or_b64 exec, exec, s[4:5]
	s_cmp_lt_u32 s85, 13
	s_cbranch_scc1 .LBB0_1305
	v_readfirstlane_b32 s3, v254
	s_cmp_lt_u32 s3, 64
	s_cbranch_scc0 .Lseam_noinv_9
	buffer_inv sc1
.Lseam_noinv_9:
	s_waitcnt vmcnt(0)
	s_waitcnt lgkmcnt(0)
	s_barrier
	s_mov_b64 s[0:1], exec
	v_readlane_b32 s4, v255, 1
	v_readlane_b32 s5, v255, 2
	s_and_b64 s[4:5], s[0:1], s[4:5]
	s_mov_b64 exec, s[4:5]
	s_cbranch_execz .LBB0_1304
	s_add_i32 s3, 0, 0x23fc0
	v_mov_b32_e32 v0, s3
	s_waitcnt vmcnt(0) expcnt(0) lgkmcnt(0)
	ds_read_b32 v2, v0
	s_add_i32 s3, 0, 0x23fc4
	v_mov_b32_e32 v0, s3
	ds_read_b32 v0, v0
	s_waitcnt lgkmcnt(1)
	v_cmp_ne_u32_e32 vcc, 0, v2
	s_cbranch_vccnz .LBB0_1268
	s_add_u32 s4, s30, 0x80200
	s_addc_u32 s5, s31, 0
	s_add_u32 s6, s30, 0x80400
	s_addc_u32 s7, s31, 0
	s_add_u32 s8, s30, 0x80500
	s_addc_u32 s9, s31, 0
	s_add_u32 s10, s30, 0x80600
	s_addc_u32 s11, s31, 0
	s_add_u32 s12, s30, 0x80700
	s_addc_u32 s13, s31, 0
	s_add_u32 s14, s30, 0x80800
	s_addc_u32 s15, s31, 0
	s_add_u32 s16, s30, 0x80900
	s_addc_u32 s17, s31, 0
	s_add_u32 s18, s30, 0x80a00
	s_addc_u32 s19, s31, 0
	s_add_u32 s20, s30, 0x80b00
	s_addc_u32 s21, s31, 0
	s_add_u32 s22, s30, 0x80c00
	s_addc_u32 s23, s31, 0
	s_add_u32 s24, s30, 0x80d00
	s_addc_u32 s25, s31, 0
	s_add_u32 s26, s30, 0x80e00
	s_addc_u32 s27, s31, 0
	s_add_u32 s36, s30, 0x80f00
	s_addc_u32 s37, s31, 0
	s_add_u32 s38, s30, 0x81000
	s_addc_u32 s39, s31, 0
	s_add_u32 s40, s30, 0x81100
	s_addc_u32 s41, s31, 0
	s_add_u32 s42, s30, 0x81200
	v_readlane_b32 s3, v255, 0
	s_addc_u32 s43, s31, 0
	s_mul_i32 s3, s87, s3
	s_add_u32 s48, s30, 0x81300
	s_mul_i32 s3, s3, s86
	s_addc_u32 s49, s31, 0
	s_mov_b32 s28, 1
	v_mov_b32_e32 v16, 0
	s_branch .LBB0_1256

; __device__ __forceinline__ unsigned xb_ld(unsigned* p)              { return __hip_atomic_load(p, __ATOMIC_RELAXED, __HIP_MEMORY_SCOPE_AGENT); }
; __device__ __forceinline__ void xcd_barrier_complete(unsigned* bar, unsigned x, unsigned& nloc, unsigned& nx) {
;     const unsigned G = gridDim.x * gridDim.y * gridDim.z;
;     unsigned sum, cnt, mine, sp = 0u;
;     for (;;) {
;         sum = 0u; cnt = 0u; mine = 0u;
; #pragma unroll
;         for (unsigned j = 0; j < 16; ++j) { const unsigned c = xb_ld(&bar[XB_XCNT(j)]); sum += c; cnt += (c > 0u) ? 1u : 0u; mine = (j == x) ? c : mine; }
; __device__ __forceinline__ void xcd_barrier(const XcdBarrier& b) {
;     asm volatile("s_waitcnt vmcnt(0)" ::: "memory");
;     __syncthreads();
;     if (threadIdx.x == 0) {
;         unsigned* bar = b.bar;
;         __builtin_amdgcn_s_waitcnt(0);
;         unsigned nloc = b.st[0], nx = b.st[1];
;         if (nloc == 0u) { xcd_barrier_complete(bar, b.x, nloc, nx); b.st[0] = nloc; b.st[1] = nx; }
.LBB0_1338:
	s_cmp_lt_i32 s85, 14
	s_cbranch_scc1 .LBB0_1392
	v_readfirstlane_b32 s3, v254
	s_cmp_lt_u32 s3, 64
	s_cbranch_scc0 .Lseam_noinv_10
	buffer_inv sc1
.Lseam_noinv_10:
	s_waitcnt vmcnt(0)
	s_waitcnt vmcnt(0) lgkmcnt(0)
	s_barrier
	s_mov_b64 s[0:1], exec
	v_readlane_b32 s4, v255, 1
	v_readlane_b32 s5, v255, 2
	s_and_b64 s[4:5], s[0:1], s[4:5]
	s_mov_b64 exec, s[4:5]
	s_cbranch_execz .LBB0_1391
	s_add_i32 s3, 0, 0x23fc0
	v_mov_b32_e32 v0, s3
	s_waitcnt vmcnt(0) expcnt(0) lgkmcnt(0)
	ds_read_b32 v2, v0
	s_add_i32 s3, 0, 0x23fc4
	v_mov_b32_e32 v0, s3
	ds_read_b32 v0, v0
	s_waitcnt lgkmcnt(1)
	v_cmp_ne_u32_e32 vcc, 0, v2
	s_cbranch_vccnz .LBB0_1355
	s_add_u32 s4, s30, 0x80200
	s_addc_u32 s5, s31, 0
	s_add_u32 s6, s30, 0x80400
	s_addc_u32 s7, s31, 0
	s_add_u32 s8, s30, 0x80500
	s_addc_u32 s9, s31, 0
	s_add_u32 s10, s30, 0x80600
	s_addc_u32 s11, s31, 0
	s_add_u32 s12, s30, 0x80700
	s_addc_u32 s13, s31, 0
	s_add_u32 s14, s30, 0x80800
	s_addc_u32 s15, s31, 0
	s_add_u32 s16, s30, 0x80900
	s_addc_u32 s17, s31, 0
	s_add_u32 s18, s30, 0x80a00
	s_addc_u32 s19, s31, 0
	s_add_u32 s20, s30, 0x80b00
	s_addc_u32 s21, s31, 0
	s_add_u32 s22, s30, 0x80c00
	s_addc_u32 s23, s31, 0
	s_add_u32 s24, s30, 0x80d00
	s_addc_u32 s25, s31, 0
	s_add_u32 s26, s30, 0x80e00
	s_addc_u32 s27, s31, 0
	s_add_u32 s36, s30, 0x80f00
	s_addc_u32 s37, s31, 0
	s_add_u32 s38, s30, 0x81000
	s_addc_u32 s39, s31, 0
	s_add_u32 s40, s30, 0x81100
	s_addc_u32 s41, s31, 0
	s_add_u32 s42, s30, 0x81200
	v_readlane_b32 s3, v255, 0
	s_addc_u32 s43, s31, 0
	s_mul_i32 s3, s87, s3
	s_add_u32 s48, s30, 0x81300
	s_mul_i32 s3, s3, s86
	s_addc_u32 s49, s31, 0
	s_mov_b32 s28, 1
	v_mov_b32_e32 v16, 0
	s_branch .LBB0_1343

; __device__ __forceinline__ unsigned xb_ld(unsigned* p)              { return __hip_atomic_load(p, __ATOMIC_RELAXED, __HIP_MEMORY_SCOPE_AGENT); }
; __device__ __forceinline__ void xcd_barrier_complete(unsigned* bar, unsigned x, unsigned& nloc, unsigned& nx) {
;     const unsigned G = gridDim.x * gridDim.y * gridDim.z;
;     unsigned sum, cnt, mine, sp = 0u;
;     for (;;) {
;         sum = 0u; cnt = 0u; mine = 0u;
; #pragma unroll
;         for (unsigned j = 0; j < 16; ++j) { const unsigned c = xb_ld(&bar[XB_XCNT(j)]); sum += c; cnt += (c > 0u) ? 1u : 0u; mine = (j == x) ? c : mine; }
; __device__ __forceinline__ void xcd_barrier(const XcdBarrier& b) {
;     asm volatile("s_waitcnt vmcnt(0)" ::: "memory");
;     __syncthreads();
;     if (threadIdx.x == 0) {
;         unsigned* bar = b.bar;
;         __builtin_amdgcn_s_waitcnt(0);
;         unsigned nloc = b.st[0], nx = b.st[1];
;         if (nloc == 0u) { xcd_barrier_complete(bar, b.x, nloc, nx); b.st[0] = nloc; b.st[1] = nx; }
.LBB0_1404:
	s_or_b64 exec, exec, s[4:5]
	s_cmp_lt_i32 s85, 15
	s_cbranch_scc1 .LBB0_1458
	v_readfirstlane_b32 s3, v254
	s_cmp_lt_u32 s3, 64
	s_cbranch_scc0 .Lseam_noinv_11
	buffer_inv sc1
.Lseam_noinv_11:
	s_waitcnt vmcnt(0)
	s_waitcnt vmcnt(0) lgkmcnt(0)
	s_barrier
	s_mov_b64 s[0:1], exec
	v_readlane_b32 s4, v255, 1
	v_readlane_b32 s5, v255, 2
	s_and_b64 s[4:5], s[0:1], s[4:5]
	s_mov_b64 exec, s[4:5]
	s_cbranch_execz .LBB0_1457
	s_add_i32 s3, 0, 0x23fc0
	v_mov_b32_e32 v0, s3
	s_waitcnt vmcnt(0) expcnt(0) lgkmcnt(0)
	ds_read_b32 v2, v0
	s_add_i32 s3, 0, 0x23fc4
	v_mov_b32_e32 v0, s3
	ds_read_b32 v0, v0
	s_waitcnt lgkmcnt(1)
	v_cmp_ne_u32_e32 vcc, 0, v2
	s_cbranch_vccnz .LBB0_1421
	s_add_u32 s4, s30, 0x80200
	s_addc_u32 s5, s31, 0
	s_add_u32 s6, s30, 0x80400
	s_addc_u32 s7, s31, 0
	s_add_u32 s8, s30, 0x80500
	s_addc_u32 s9, s31, 0
	s_add_u32 s10, s30, 0x80600
	s_addc_u32 s11, s31, 0
	s_add_u32 s12, s30, 0x80700
	s_addc_u32 s13, s31, 0
	s_add_u32 s14, s30, 0x80800
	s_addc_u32 s15, s31, 0
	s_add_u32 s16, s30, 0x80900
	s_addc_u32 s17, s31, 0
	s_add_u32 s18, s30, 0x80a00
	s_addc_u32 s19, s31, 0
	s_add_u32 s20, s30, 0x80b00
	s_addc_u32 s21, s31, 0
	s_add_u32 s22, s30, 0x80c00
	s_addc_u32 s23, s31, 0
	s_add_u32 s24, s30, 0x80d00
	s_addc_u32 s25, s31, 0
	s_add_u32 s26, s30, 0x80e00
	s_addc_u32 s27, s31, 0
	s_add_u32 s36, s30, 0x80f00
	s_addc_u32 s37, s31, 0
	s_add_u32 s38, s30, 0x81000
	s_addc_u32 s39, s31, 0
	s_add_u32 s40, s30, 0x81100
	s_addc_u32 s41, s31, 0
	s_add_u32 s42, s30, 0x81200
	v_readlane_b32 s3, v255, 0
	s_addc_u32 s43, s31, 0
	s_mul_i32 s3, s87, s3
	s_add_u32 s44, s30, 0x81300
	s_mul_i32 s3, s3, s86
	s_addc_u32 s45, s31, 0
	s_mov_b32 s28, 1
	v_mov_b32_e32 v16, 0
	s_branch .LBB0_1409

; __device__ __forceinline__ unsigned xb_ld(unsigned* p)              { return __hip_atomic_load(p, __ATOMIC_RELAXED, __HIP_MEMORY_SCOPE_AGENT); }
; __device__ __forceinline__ void xcd_barrier_complete(unsigned* bar, unsigned x, unsigned& nloc, unsigned& nx) {
;     const unsigned G = gridDim.x * gridDim.y * gridDim.z;
;     unsigned sum, cnt, mine, sp = 0u;
;     for (;;) {
;         sum = 0u; cnt = 0u; mine = 0u;
; #pragma unroll
;         for (unsigned j = 0; j < 16; ++j) { const unsigned c = xb_ld(&bar[XB_XCNT(j)]); sum += c; cnt += (c > 0u) ? 1u : 0u; mine = (j == x) ? c : mine; }
; __device__ __forceinline__ void xcd_barrier(const XcdBarrier& b) {
;     asm volatile("s_waitcnt vmcnt(0)" ::: "memory");
;     __syncthreads();
;     if (threadIdx.x == 0) {
;         unsigned* bar = b.bar;
;         __builtin_amdgcn_s_waitcnt(0);
;         unsigned nloc = b.st[0], nx = b.st[1];
;         if (nloc == 0u) { xcd_barrier_complete(bar, b.x, nloc, nx); b.st[0] = nloc; b.st[1] = nx; }
.LBB0_1487:
	s_cmp_lt_i32 s85, 18
	s_cbranch_scc1 .LBB0_1541
	v_readfirstlane_b32 s3, v254
	s_cmp_lt_u32 s3, 64
	s_cbranch_scc0 .Lseam_noinv_12
	buffer_inv sc1
.Lseam_noinv_12:
	s_waitcnt vmcnt(0)
	s_waitcnt vmcnt(0) lgkmcnt(0)
	s_barrier
	s_mov_b64 s[0:1], exec
	v_readlane_b32 s2, v255, 1
	v_readlane_b32 s3, v255, 2
	s_and_b64 s[2:3], s[0:1], s[2:3]
	s_mov_b64 exec, s[2:3]
	s_cbranch_execz .LBB0_1540
	s_add_i32 s2, 0, 0x23fc0
	v_mov_b32_e32 v0, s2
	s_waitcnt vmcnt(0) expcnt(0) lgkmcnt(0)
	ds_read_b32 v2, v0
	s_add_i32 s2, 0, 0x23fc4
	v_mov_b32_e32 v0, s2
	ds_read_b32 v0, v0
	s_waitcnt lgkmcnt(1)
	v_cmp_ne_u32_e32 vcc, 0, v2
	s_cbranch_vccnz .LBB0_1504
	v_readlane_b32 s2, v255, 0
	s_mul_i32 s33, s87, s2
	s_add_u32 s2, s30, 0x80200
	s_addc_u32 s3, s31, 0
	s_add_u32 s4, s30, 0x80400
	s_addc_u32 s5, s31, 0
	s_add_u32 s6, s30, 0x80500
	s_addc_u32 s7, s31, 0
	s_add_u32 s8, s30, 0x80600
	s_addc_u32 s9, s31, 0
	s_add_u32 s10, s30, 0x80700
	s_addc_u32 s11, s31, 0
	s_add_u32 s12, s30, 0x80800
	s_addc_u32 s13, s31, 0
	s_add_u32 s14, s30, 0x80900
	s_addc_u32 s15, s31, 0
	s_add_u32 s16, s30, 0x80a00
	s_addc_u32 s17, s31, 0
	s_add_u32 s18, s30, 0x80b00
	s_addc_u32 s19, s31, 0
	s_add_u32 s20, s30, 0x80c00
	s_addc_u32 s21, s31, 0
	s_add_u32 s22, s30, 0x80d00
	s_addc_u32 s23, s31, 0
	s_add_u32 s24, s30, 0x80e00
	s_addc_u32 s25, s31, 0
	s_add_u32 s26, s30, 0x80f00
	s_addc_u32 s27, s31, 0
	s_add_u32 s28, s30, 0x81000
	s_addc_u32 s29, s31, 0
	s_add_u32 s36, s30, 0x81100
	s_addc_u32 s37, s31, 0
	s_add_u32 s38, s30, 0x81200
	s_addc_u32 s39, s31, 0
	s_add_u32 s40, s30, 0x81300
	s_mul_i32 s33, s33, s86
	s_addc_u32 s41, s31, 0
	s_mov_b32 s34, 1
	v_mov_b32_e32 v16, 0
	s_branch .LBB0_1492
